# P1 first norm: 16 dwordx2 stores per 4 rows widened to 8 dwordx4 via adjacent-lane exchange (v_cndmask_b32_dpp), same bytes
# baseline (speedup 1.0000x reference)
; __device__ __forceinline__ void norm_rows(const float* x, int nrows, const float* g, const float* sc, const float* sh, bf16_t* o, int lane) {
;     ...
;     for (; r0 + 4 <= nrows; r0 += 4) {
;         f32x4 v[4][4];
; #pragma unroll
;         for (int rr = 0; rr < 4; ++rr) { const f32x4* xr = (const f32x4*)(x + (size_t)(r0 + rr) * 1024) + lane;
; #pragma unroll
;             for (int j = 0; j < 4; ++j) v[rr][j] = xr[64 * j]; }
; #pragma unroll
;         for (int rr = 0; rr < 4; ++rr) { float ss = 0.f;
; #pragma unroll
;             for (int j = 0; j < 4; ++j) ss += (v[rr][j].x * v[rr][j].x + v[rr][j].y * v[rr][j].y) + (v[rr][j].z * v[rr][j].z + v[rr][j].w * v[rr][j].w);
.LBB0_316:
	s_mov_b32 s56, 0x55555555
	s_mov_b32 s57, 0x55555555
	s_mov_b32 s58, 0xaaaaaaaa
	s_mov_b32 s59, 0xaaaaaaaa
	v_and_b32_e32 v178, 1, v152
	v_mul_u32_u24_e32 v178, 0x1f8, v178
	v_mov_b32_e32 v179, 0
	v_add_co_u32_e32 v78, vcc, 0xffffd000, v56
	global_load_dwordx4 v[28:31], v[56:57], off offset:-3072
	global_load_dwordx4 v[24:27], v[56:57], off offset:-2048
	global_load_dwordx4 v[20:23], v[56:57], off offset:-1024
	global_load_dwordx4 v[16:19], v[56:57], off
	v_addc_co_u32_e32 v79, vcc, -1, v57, vcc
	v_add_co_u32_e32 v114, vcc, 0xffffe000, v56
	global_load_dwordx4 v[86:89], v[78:79], off offset:-3072
	global_load_dwordx4 v[90:93], v[78:79], off offset:-2048
	global_load_dwordx4 v[94:97], v[78:79], off
	global_load_dwordx4 v[98:101], v[78:79], off offset:-1024
	v_addc_co_u32_e32 v115, vcc, -1, v57, vcc
	global_load_dwordx4 v[102:105], v[114:115], off offset:-3072
	global_load_dwordx4 v[106:109], v[114:115], off offset:-2048
	global_load_dwordx4 v[110:113], v[114:115], off
	s_nop 0
	global_load_dwordx4 v[114:117], v[114:115], off offset:-1024
	v_add_co_u32_e32 v78, vcc, 0xfffff000, v56
	v_mov_b64_e32 v[76:77], s[38:39]
	s_nop 0
	v_addc_co_u32_e32 v79, vcc, -1, v57, vcc
	global_load_dwordx4 v[118:121], v[78:79], off offset:-3072
	global_load_dwordx4 v[122:125], v[78:79], off offset:-2048
	global_load_dwordx4 v[126:129], v[56:57], off offset:-4096
	global_load_dwordx4 v[130:133], v[78:79], off offset:-1024
	v_add_co_u32_e64 v74, s[0:1], s25, v54
	s_add_i32 s47, s47, 4
	s_nop 0
	v_addc_co_u32_e64 v75, s[0:1], -1, v55, s[0:1]
	s_cmp_lt_u32 s47, 32
	v_lshl_add_u64 v[56:57], v[56:57], 0, s[44:45]
	s_waitcnt vmcnt(15)
	v_pk_mul_f32 v[78:79], v[30:31], v[30:31]
	v_pk_mul_f32 v[134:135], v[28:29], v[28:29]
	s_waitcnt vmcnt(14)
	v_pk_mul_f32 v[136:137], v[26:27], v[26:27]
	v_pk_mul_f32 v[138:139], v[24:25], v[24:25]
	s_waitcnt vmcnt(13)
	v_mul_f32_e32 v140, v21, v21
	v_mul_f32_e32 v142, v23, v23
	s_waitcnt vmcnt(12)
	v_mul_f32_e32 v51, v18, v18
	v_mul_f32_e32 v153, v19, v19
	v_pk_mov_b32 v[144:145], v[134:135], v[78:79] op_sel:[1,0]
	v_mov_b32_e32 v135, v79
	v_pk_mov_b32 v[78:79], v[138:139], v[136:137] op_sel:[1,0]
	v_mov_b32_e32 v139, v137
	v_pk_fma_f32 v[136:137], v[20:21], v[20:21], v[140:141] op_sel_hi:[1,1,0]
	v_pk_fma_f32 v[140:141], v[22:23], v[22:23], v[142:143] op_sel_hi:[1,1,0]
	s_waitcnt vmcnt(11)
	v_pk_mul_f32 v[142:143], v[88:89], v[88:89]
	v_pk_mul_f32 v[146:147], v[86:87], v[86:87]
	s_waitcnt vmcnt(10)
	v_pk_mul_f32 v[148:149], v[92:93], v[92:93]
	v_pk_mul_f32 v[150:151], v[90:91], v[90:91]
	s_waitcnt vmcnt(8)
	v_mul_f32_e32 v154, v99, v99
	v_mul_f32_e32 v156, v101, v101
	v_mul_f32_e32 v163, v96, v96
	v_mul_f32_e32 v165, v97, v97
	v_pk_add_f32 v[134:135], v[144:145], v[134:135]
	v_pk_add_f32 v[78:79], v[78:79], v[138:139]
	v_mov_b32_e32 v137, v51
	v_mov_b32_e32 v141, v153
	v_pk_mov_b32 v[138:139], v[146:147], v[142:143] op_sel:[1,0]
	v_mov_b32_e32 v147, v143
	v_pk_mov_b32 v[142:143], v[150:151], v[148:149] op_sel:[1,0]
	v_mov_b32_e32 v151, v149
	v_pk_fma_f32 v[144:145], v[98:99], v[98:99], v[154:155] op_sel_hi:[1,1,0]
	v_pk_fma_f32 v[148:149], v[100:101], v[100:101], v[156:157] op_sel_hi:[1,1,0]
	s_waitcnt vmcnt(7)
	v_pk_mul_f32 v[154:155], v[104:105], v[104:105]
	v_pk_mul_f32 v[156:157], v[102:103], v[102:103]
	s_waitcnt vmcnt(6)
	v_pk_mul_f32 v[158:159], v[108:109], v[108:109]
	v_pk_mul_f32 v[160:161], v[106:107], v[106:107]
	s_waitcnt vmcnt(4)
	v_mul_f32_e32 v162, v115, v115
	v_mul_f32_e32 v164, v117, v117
	v_mul_f32_e32 v37, v16, v16
	v_mul_f32_e32 v39, v17, v17
	v_mul_f32_e32 v172, v112, v112
	v_mul_f32_e32 v173, v113, v113
	v_pk_add_f32 v[134:135], v[134:135], v[134:135] op_sel:[0,1] op_sel_hi:[1,0]
	v_pk_add_f32 v[78:79], v[78:79], v[78:79] op_sel:[0,1] op_sel_hi:[1,0]
	v_pk_add_f32 v[136:137], v[136:137], v[140:141]
	v_pk_add_f32 v[138:139], v[138:139], v[146:147]
	v_pk_add_f32 v[140:141], v[142:143], v[150:151]
	v_mov_b32_e32 v145, v163
	v_mov_b32_e32 v149, v165
	v_pk_mov_b32 v[142:143], v[156:157], v[154:155] op_sel:[1,0]
	v_mov_b32_e32 v157, v155
	v_pk_mov_b32 v[146:147], v[160:161], v[158:159] op_sel:[1,0]
	v_mov_b32_e32 v161, v159
	v_pk_fma_f32 v[150:151], v[114:115], v[114:115], v[162:163] op_sel_hi:[1,1,0]
	v_pk_fma_f32 v[154:155], v[116:117], v[116:117], v[164:165] op_sel_hi:[1,1,0]
	s_waitcnt vmcnt(3)
	v_pk_mul_f32 v[158:159], v[120:121], v[120:121]
	v_pk_mul_f32 v[162:163], v[118:119], v[118:119]
	s_waitcnt vmcnt(2)
	v_pk_mul_f32 v[164:165], v[124:125], v[124:125]
	v_pk_mul_f32 v[166:167], v[122:123], v[122:123]
	v_mul_f32_e32 v169, v94, v94
	v_mul_f32_e32 v171, v95, v95
	v_mov_b32_e32 v135, v37
	v_mov_b32_e32 v79, v39
	v_pk_add_f32 v[138:139], v[138:139], v[138:139] op_sel:[0,1] op_sel_hi:[1,0]
	v_pk_add_f32 v[140:141], v[140:141], v[140:141] op_sel:[0,1] op_sel_hi:[1,0]
	v_pk_add_f32 v[144:145], v[144:145], v[148:149]
	v_pk_add_f32 v[142:143], v[142:143], v[156:157]
	v_pk_add_f32 v[146:147], v[146:147], v[160:161]
	v_mov_b32_e32 v151, v172
	v_mov_b32_e32 v155, v173
	v_pk_mov_b32 v[148:149], v[162:163], v[158:159] op_sel:[1,0]
	v_mov_b32_e32 v163, v159
	v_pk_mov_b32 v[156:157], v[166:167], v[164:165] op_sel:[1,0]
	v_mov_b32_e32 v167, v165
	v_mul_f32_e32 v51, v110, v110
	v_mul_f32_e32 v153, v111, v111
	s_waitcnt vmcnt(0)
; __device__ __forceinline__ unsigned pk2(float lo, float hi) { f32x2 v = {lo, hi}; bf16x2_t b = __builtin_convertvector(v, bf16x2_t); return __builtin_bit_cast(unsigned, b); }
; __device__ __forceinline__ float wave_sum(float v) {
; #pragma unroll
;     for (int o = 1; o < 64; o <<= 1) v += __shfl_xor(v, o);
;     return v;
; }
; __device__ __forceinline__ void norm_rows(const float* x, int nrows, const float* g, const float* sc, const float* sh, bf16_t* o, int lane) {
;     ...
;         for (int rr = 0; rr < 4; ++rr) { float ss = 0.f;
; #pragma unroll
;             for (int j = 0; j < 4; ++j) ss += (v[rr][j].x * v[rr][j].x + v[rr][j].y * v[rr][j].y) + (v[rr][j].z * v[rr][j].z + v[rr][j].w * v[rr][j].w);
;             const float rstd = rsqrtf(wave_sum(ss) * (1.0f / 1024.0f) + 1e-6f);
;             u32x2* op = (u32x2*)(o + (size_t)(r0 + rr) * 1024) + lane;
; #pragma unroll
;             for (int j = 0; j < 4; ++j) { const f32x4 y = v[rr][j] * rstd * gs[j] + shv[j]; u32x2 wv; wv.x = pk2(y.x, y.y); wv.y = pk2(y.z, y.w); op[64 * j] = wv; } }
	v_mul_f32_e32 v168, v131, v131
	v_mul_f32_e32 v170, v133, v133
	v_pk_add_f32 v[78:79], v[134:135], v[78:79]
	v_mov_b32_e32 v139, v169
	v_mov_b32_e32 v141, v171
	v_pk_add_f32 v[134:135], v[142:143], v[142:143] op_sel:[0,1] op_sel_hi:[1,0]
	v_pk_add_f32 v[142:143], v[146:147], v[146:147] op_sel:[0,1] op_sel_hi:[1,0]
	v_pk_add_f32 v[146:147], v[150:151], v[154:155]
	v_pk_add_f32 v[148:149], v[148:149], v[162:163]
	v_pk_add_f32 v[150:151], v[156:157], v[166:167]
	v_mul_f32_e32 v174, v126, v126
	v_mul_f32_e32 v175, v127, v127
	v_mul_f32_e32 v176, v128, v128
	v_mul_f32_e32 v177, v129, v129
	v_pk_fma_f32 v[158:159], v[130:131], v[130:131], v[168:169] op_sel_hi:[1,1,0]
	v_pk_fma_f32 v[160:161], v[132:133], v[132:133], v[170:171] op_sel_hi:[1,1,0]
	v_pk_add_f32 v[78:79], v[78:79], v[136:137]
	v_pk_add_f32 v[136:137], v[138:139], v[140:141]
	v_mov_b32_e32 v135, v51
	v_mov_b32_e32 v143, v153
	v_pk_add_f32 v[138:139], v[148:149], v[148:149] op_sel:[0,1] op_sel_hi:[1,0]
	v_pk_add_f32 v[140:141], v[150:151], v[150:151] op_sel:[0,1] op_sel_hi:[1,0]
	v_mov_b32_e32 v159, v176
	v_mov_b32_e32 v161, v177
	v_pk_add_f32 v[134:135], v[134:135], v[142:143]
	v_mov_b32_e32 v139, v174
	v_mov_b32_e32 v141, v175
	v_pk_add_f32 v[148:149], v[158:159], v[160:161]
	v_pk_add_f32 v[136:137], v[136:137], v[144:145]
	v_pk_add_f32 v[134:135], v[134:135], v[146:147]
	v_pk_add_f32 v[138:139], v[138:139], v[140:141]
	v_mov_b32_e32 v143, v136
	v_mov_b32_e32 v142, v134
	v_mov_b32_e32 v136, v135
	v_pk_add_f32 v[134:135], v[138:139], v[148:149]
	v_mov_b32_e32 v150, v78
	v_pk_add_f32 v[136:137], v[142:143], v[136:137]
	v_mov_b32_e32 v151, v134
	v_mov_b32_e32 v134, v79
	ds_bpermute_b32 v79, v80, v137
	ds_bpermute_b32 v78, v80, v136
	v_pk_add_f32 v[134:135], v[150:151], v[134:135]
	ds_bpermute_b32 v139, v80, v135
	ds_bpermute_b32 v138, v80, v134
	s_waitcnt lgkmcnt(2)
	v_pk_add_f32 v[78:79], v[136:137], v[78:79]
	ds_bpermute_b32 v137, v81, v79
	ds_bpermute_b32 v136, v81, v78
	s_waitcnt lgkmcnt(2)
	v_pk_add_f32 v[134:135], v[134:135], v[138:139]
	ds_bpermute_b32 v139, v81, v135
	ds_bpermute_b32 v138, v81, v134
	s_waitcnt lgkmcnt(2)
	v_pk_add_f32 v[78:79], v[78:79], v[136:137]
	ds_bpermute_b32 v137, v82, v79
	ds_bpermute_b32 v136, v82, v78
	s_waitcnt lgkmcnt(2)
	v_pk_add_f32 v[134:135], v[134:135], v[138:139]
	ds_bpermute_b32 v139, v82, v135
	ds_bpermute_b32 v138, v82, v134
	s_waitcnt lgkmcnt(2)
	v_pk_add_f32 v[78:79], v[78:79], v[136:137]
	ds_bpermute_b32 v137, v83, v79
	ds_bpermute_b32 v136, v83, v78
	s_waitcnt lgkmcnt(2)
	v_pk_add_f32 v[134:135], v[134:135], v[138:139]
	ds_bpermute_b32 v139, v83, v135
	ds_bpermute_b32 v138, v83, v134
	s_waitcnt lgkmcnt(2)
	v_pk_add_f32 v[78:79], v[78:79], v[136:137]
	ds_bpermute_b32 v137, v84, v79
	ds_bpermute_b32 v136, v84, v78
	s_waitcnt lgkmcnt(2)
	v_pk_add_f32 v[134:135], v[134:135], v[138:139]
	ds_bpermute_b32 v139, v84, v135
	ds_bpermute_b32 v138, v84, v134
	s_waitcnt lgkmcnt(2)
	v_pk_add_f32 v[78:79], v[78:79], v[136:137]
	ds_bpermute_b32 v137, v85, v79
	ds_bpermute_b32 v136, v85, v78
	s_waitcnt lgkmcnt(2)
	v_pk_add_f32 v[134:135], v[134:135], v[138:139]
	ds_bpermute_b32 v139, v85, v135
	ds_bpermute_b32 v138, v85, v134
	s_waitcnt lgkmcnt(2)
	v_pk_add_f32 v[78:79], v[78:79], v[136:137]
	s_nop 0
	v_pk_fma_f32 v[78:79], v[78:79], s[24:25], v[76:77] op_sel_hi:[1,0,0]
	s_waitcnt lgkmcnt(0)
	v_pk_add_f32 v[134:135], v[134:135], v[138:139]
	v_mul_f32_e32 v37, 0x4b800000, v79
	v_mul_f32_e32 v39, 0x4b800000, v78
	v_cmp_gt_f32_e32 vcc, s39, v78
	v_pk_fma_f32 v[76:77], v[134:135], s[24:25], v[76:77] op_sel_hi:[1,0,0]
	v_cmp_gt_f32_e64 s[0:1], s39, v79
	v_cndmask_b32_e32 v39, v78, v39, vcc
	v_mul_f32_e32 v51, 0x4b800000, v77
	v_cndmask_b32_e64 v37, v79, v37, s[0:1]
	v_cmp_gt_f32_e64 s[6:7], s39, v77
	v_mul_f32_e32 v78, 0x4b800000, v76
	v_cmp_gt_f32_e64 s[4:5], s39, v76
	v_rsq_f32_e32 v37, v37
	v_rsq_f32_e32 v39, v39
	v_cndmask_b32_e64 v51, v77, v51, s[6:7]
	v_cndmask_b32_e64 v76, v76, v78, s[4:5]
	v_rsq_f32_e32 v51, v51
	v_rsq_f32_e32 v134, v76
	v_mul_f32_e32 v76, 0x45800000, v37
	v_mul_f32_e32 v77, 0x45800000, v39
	v_cndmask_b32_e64 v76, v37, v76, s[0:1]
	v_cndmask_b32_e32 v78, v39, v77, vcc
	v_mul_f32_e32 v37, 0x45800000, v51
	v_mul_f32_e32 v39, 0x45800000, v134
	v_pk_mul_f32 v[86:87], v[86:87], v[76:77] op_sel_hi:[1,0]
	v_pk_mul_f32 v[88:89], v[88:89], v[76:77] op_sel_hi:[1,0]
	v_pk_mul_f32 v[90:91], v[90:91], v[76:77] op_sel_hi:[1,0]
	v_pk_mul_f32 v[92:93], v[92:93], v[76:77] op_sel_hi:[1,0]
	v_pk_mul_f32 v[98:99], v[98:99], v[76:77] op_sel_hi:[1,0]
	v_pk_mul_f32 v[100:101], v[100:101], v[76:77] op_sel_hi:[1,0]
	v_pk_mul_f32 v[94:95], v[94:95], v[76:77] op_sel_hi:[1,0]
	v_pk_mul_f32 v[76:77], v[96:97], v[76:77] op_sel_hi:[1,0]
	v_pk_mul_f32 v[96:97], v[102:103], v[78:79] op_sel_hi:[1,0]
	v_pk_mul_f32 v[102:103], v[104:105], v[78:79] op_sel_hi:[1,0]
	v_pk_mul_f32 v[104:105], v[106:107], v[78:79] op_sel_hi:[1,0]
	v_pk_mul_f32 v[106:107], v[108:109], v[78:79] op_sel_hi:[1,0]
	v_pk_mul_f32 v[108:109], v[114:115], v[78:79] op_sel_hi:[1,0]
	v_pk_mul_f32 v[114:115], v[116:117], v[78:79] op_sel_hi:[1,0]
	v_pk_mul_f32 v[110:111], v[110:111], v[78:79] op_sel_hi:[1,0]
	v_pk_mul_f32 v[78:79], v[112:113], v[78:79] op_sel_hi:[1,0]
	v_cndmask_b32_e64 v112, v51, v37, s[6:7]
	v_cndmask_b32_e64 v116, v134, v39, s[4:5]
	v_pk_fma_f32 v[88:89], v[58:59], v[88:89], v[10:11]
	v_pk_fma_f32 v[86:87], v[60:61], v[86:87], v[8:9]
	v_pk_fma_f32 v[90:91], v[64:65], v[90:91], v[0:1]
	v_pk_fma_f32 v[100:101], v[66:67], v[100:101], v[6:7]
	v_pk_fma_f32 v[98:99], v[68:69], v[98:99], v[4:5]
	v_pk_fma_f32 v[78:79], v[70:71], v[78:79], v[14:15]
	v_pk_mul_f32 v[118:119], v[118:119], v[112:113] op_sel_hi:[1,0]
; __device__ __forceinline__ unsigned pk2(float lo, float hi) { f32x2 v = {lo, hi}; bf16x2_t b = __builtin_convertvector(v, bf16x2_t); return __builtin_bit_cast(unsigned, b); }
; __device__ __forceinline__ void norm_rows(const float* x, int nrows, const float* g, const float* sc, const float* sh, bf16_t* o, int lane) {
;     ...
;             u32x2* op = (u32x2*)(o + (size_t)(r0 + rr) * 1024) + lane;
; #pragma unroll
;             for (int j = 0; j < 4; ++j) { const f32x4 y = v[rr][j] * rstd * gs[j] + shv[j]; u32x2 wv; wv.x = pk2(y.x, y.y); wv.y = pk2(y.z, y.w); op[64 * j] = wv; } }
	v_pk_mul_f32 v[120:121], v[120:121], v[112:113] op_sel_hi:[1,0]
	v_pk_fma_f32 v[92:93], v[62:63], v[92:93], v[2:3]
	v_pk_fma_f32 v[76:77], v[70:71], v[76:77], v[14:15]
	v_pk_fma_f32 v[94:95], v[72:73], v[94:95], v[12:13]
	v_pk_fma_f32 v[102:103], v[58:59], v[102:103], v[10:11]
	v_pk_fma_f32 v[96:97], v[60:61], v[96:97], v[8:9]
	v_pk_fma_f32 v[106:107], v[62:63], v[106:107], v[2:3]
	v_pk_fma_f32 v[104:105], v[64:65], v[104:105], v[0:1]
	v_pk_fma_f32 v[114:115], v[66:67], v[114:115], v[6:7]
	v_pk_fma_f32 v[108:109], v[68:69], v[108:109], v[4:5]
	v_pk_fma_f32 v[110:111], v[72:73], v[110:111], v[12:13]
	v_pk_mul_f32 v[122:123], v[122:123], v[112:113] op_sel_hi:[1,0]
	v_pk_mul_f32 v[124:125], v[124:125], v[112:113] op_sel_hi:[1,0]
	v_pk_mul_f32 v[130:131], v[130:131], v[112:113] op_sel_hi:[1,0]
	v_pk_mul_f32 v[132:133], v[132:133], v[112:113] op_sel_hi:[1,0]
	v_pk_mul_f32 v[126:127], v[126:127], v[112:113] op_sel_hi:[1,0]
	v_pk_mul_f32 v[112:113], v[128:129], v[112:113] op_sel_hi:[1,0]
	v_pk_mul_f32 v[28:29], v[28:29], v[116:117] op_sel_hi:[1,0]
	v_pk_mul_f32 v[30:31], v[30:31], v[116:117] op_sel_hi:[1,0]
	v_pk_mul_f32 v[24:25], v[24:25], v[116:117] op_sel_hi:[1,0]
	v_pk_mul_f32 v[26:27], v[26:27], v[116:117] op_sel_hi:[1,0]
	v_pk_mul_f32 v[20:21], v[20:21], v[116:117] op_sel_hi:[1,0]
	v_pk_mul_f32 v[22:23], v[22:23], v[116:117] op_sel_hi:[1,0]
	v_pk_mul_f32 v[16:17], v[16:17], v[116:117] op_sel_hi:[1,0]
	v_pk_mul_f32 v[18:19], v[18:19], v[116:117] op_sel_hi:[1,0]
	v_cvt_pk_bf16_f32 v86, v86, v87
	v_cvt_pk_bf16_f32 v87, v88, v89
	v_cvt_pk_bf16_f32 v88, v90, v91
	v_cvt_pk_bf16_f32 v90, v98, v99
	v_cvt_pk_bf16_f32 v91, v100, v101
	v_cvt_pk_bf16_f32 v99, v78, v79
	v_pk_fma_f32 v[78:79], v[58:59], v[120:121], v[10:11]
	v_pk_fma_f32 v[100:101], v[60:61], v[118:119], v[8:9]
	v_cvt_pk_bf16_f32 v89, v92, v93
	v_cvt_pk_bf16_f32 v92, v94, v95
	v_cvt_pk_bf16_f32 v93, v76, v77
	v_cvt_pk_bf16_f32 v76, v96, v97
	v_cvt_pk_bf16_f32 v77, v102, v103
	v_cvt_pk_bf16_f32 v94, v104, v105
	v_cvt_pk_bf16_f32 v95, v106, v107
	v_cvt_pk_bf16_f32 v96, v108, v109
	v_cvt_pk_bf16_f32 v97, v114, v115
	v_cvt_pk_bf16_f32 v98, v110, v111
	v_pk_fma_f32 v[102:103], v[62:63], v[124:125], v[2:3]
	v_pk_fma_f32 v[104:105], v[64:65], v[122:123], v[0:1]
	v_pk_fma_f32 v[106:107], v[66:67], v[132:133], v[6:7]
	v_pk_fma_f32 v[108:109], v[68:69], v[130:131], v[4:5]
	v_pk_fma_f32 v[110:111], v[70:71], v[112:113], v[14:15]
	v_pk_fma_f32 v[112:113], v[72:73], v[126:127], v[12:13]
	v_pk_fma_f32 v[30:31], v[58:59], v[30:31], v[10:11]
	v_pk_fma_f32 v[28:29], v[60:61], v[28:29], v[8:9]
	v_pk_fma_f32 v[26:27], v[62:63], v[26:27], v[2:3]
	v_pk_fma_f32 v[24:25], v[64:65], v[24:25], v[0:1]
	v_pk_fma_f32 v[22:23], v[66:67], v[22:23], v[6:7]
	v_pk_fma_f32 v[20:21], v[68:69], v[20:21], v[4:5]
	v_pk_fma_f32 v[18:19], v[70:71], v[18:19], v[14:15]
	v_pk_fma_f32 v[16:17], v[72:73], v[16:17], v[12:13]
	v_lshl_add_u64 v[180:181], v[74:75], 0, v[178:179]
	s_mov_b64 vcc, s[56:57]
	v_cndmask_b32_dpp v184, v88, v86, vcc quad_perm:[1,0,3,2] row_mask:0xf bank_mask:0xf
	v_cndmask_b32_dpp v185, v89, v87, vcc quad_perm:[1,0,3,2] row_mask:0xf bank_mask:0xf
	v_cndmask_b32_dpp v188, v92, v90, vcc quad_perm:[1,0,3,2] row_mask:0xf bank_mask:0xf
	v_cndmask_b32_dpp v189, v93, v91, vcc quad_perm:[1,0,3,2] row_mask:0xf bank_mask:0xf
	v_cndmask_b32_dpp v192, v94, v76, vcc quad_perm:[1,0,3,2] row_mask:0xf bank_mask:0xf
	v_cndmask_b32_dpp v193, v95, v77, vcc quad_perm:[1,0,3,2] row_mask:0xf bank_mask:0xf
	v_cndmask_b32_dpp v196, v98, v96, vcc quad_perm:[1,0,3,2] row_mask:0xf bank_mask:0xf
	v_cndmask_b32_dpp v197, v99, v97, vcc quad_perm:[1,0,3,2] row_mask:0xf bank_mask:0xf
	s_mov_b64 vcc, s[58:59]
	v_cndmask_b32_dpp v186, v86, v88, vcc quad_perm:[1,0,3,2] row_mask:0xf bank_mask:0xf
	v_cndmask_b32_dpp v187, v87, v89, vcc quad_perm:[1,0,3,2] row_mask:0xf bank_mask:0xf
	v_cndmask_b32_dpp v190, v90, v92, vcc quad_perm:[1,0,3,2] row_mask:0xf bank_mask:0xf
	v_cndmask_b32_dpp v191, v91, v93, vcc quad_perm:[1,0,3,2] row_mask:0xf bank_mask:0xf
	v_cndmask_b32_dpp v194, v76, v94, vcc quad_perm:[1,0,3,2] row_mask:0xf bank_mask:0xf
	v_cndmask_b32_dpp v195, v77, v95, vcc quad_perm:[1,0,3,2] row_mask:0xf bank_mask:0xf
	v_cndmask_b32_dpp v198, v96, v98, vcc quad_perm:[1,0,3,2] row_mask:0xf bank_mask:0xf
	v_cndmask_b32_dpp v199, v97, v99, vcc quad_perm:[1,0,3,2] row_mask:0xf bank_mask:0xf
	global_store_dwordx4 v[180:181], v[184:187], off offset:-3584
	global_store_dwordx4 v[180:181], v[188:191], off offset:-2560
	global_store_dwordx4 v[180:181], v[192:195], off offset:-1536
	global_store_dwordx4 v[180:181], v[196:199], off offset:-512
	v_cvt_pk_bf16_f32 v74, v100, v101
	v_cvt_pk_bf16_f32 v75, v78, v79
	v_cvt_pk_bf16_f32 v76, v104, v105
	v_cvt_pk_bf16_f32 v77, v102, v103
	v_cvt_pk_bf16_f32 v78, v108, v109
	v_cvt_pk_bf16_f32 v79, v106, v107
	v_cvt_pk_bf16_f32 v86, v112, v113
	v_cvt_pk_bf16_f32 v87, v110, v111
	v_cvt_pk_bf16_f32 v28, v28, v29
	v_cvt_pk_bf16_f32 v29, v30, v31
	v_cvt_pk_bf16_f32 v24, v24, v25
	v_cvt_pk_bf16_f32 v25, v26, v27
	v_cvt_pk_bf16_f32 v20, v20, v21
	v_cvt_pk_bf16_f32 v21, v22, v23
	v_cvt_pk_bf16_f32 v16, v16, v17
	v_cvt_pk_bf16_f32 v17, v18, v19
	v_lshl_add_u64 v[182:183], v[54:55], 0, v[178:179]
	s_nop 1
	s_mov_b64 vcc, s[56:57]
	v_cndmask_b32_dpp v200, v76, v74, vcc quad_perm:[1,0,3,2] row_mask:0xf bank_mask:0xf
	v_cndmask_b32_dpp v201, v77, v75, vcc quad_perm:[1,0,3,2] row_mask:0xf bank_mask:0xf
	v_cndmask_b32_dpp v204, v86, v78, vcc quad_perm:[1,0,3,2] row_mask:0xf bank_mask:0xf
	v_cndmask_b32_dpp v205, v87, v79, vcc quad_perm:[1,0,3,2] row_mask:0xf bank_mask:0xf
	v_cndmask_b32_dpp v208, v24, v28, vcc quad_perm:[1,0,3,2] row_mask:0xf bank_mask:0xf
	v_cndmask_b32_dpp v209, v25, v29, vcc quad_perm:[1,0,3,2] row_mask:0xf bank_mask:0xf
	v_cndmask_b32_dpp v212, v16, v20, vcc quad_perm:[1,0,3,2] row_mask:0xf bank_mask:0xf
	v_cndmask_b32_dpp v213, v17, v21, vcc quad_perm:[1,0,3,2] row_mask:0xf bank_mask:0xf
	s_mov_b64 vcc, s[58:59]
	v_cndmask_b32_dpp v202, v74, v76, vcc quad_perm:[1,0,3,2] row_mask:0xf bank_mask:0xf
	v_cndmask_b32_dpp v203, v75, v77, vcc quad_perm:[1,0,3,2] row_mask:0xf bank_mask:0xf
	v_cndmask_b32_dpp v206, v78, v86, vcc quad_perm:[1,0,3,2] row_mask:0xf bank_mask:0xf
	v_cndmask_b32_dpp v207, v79, v87, vcc quad_perm:[1,0,3,2] row_mask:0xf bank_mask:0xf
	v_cndmask_b32_dpp v210, v28, v24, vcc quad_perm:[1,0,3,2] row_mask:0xf bank_mask:0xf
	v_cndmask_b32_dpp v211, v29, v25, vcc quad_perm:[1,0,3,2] row_mask:0xf bank_mask:0xf
	v_cndmask_b32_dpp v214, v20, v16, vcc quad_perm:[1,0,3,2] row_mask:0xf bank_mask:0xf
	v_cndmask_b32_dpp v215, v21, v17, vcc quad_perm:[1,0,3,2] row_mask:0xf bank_mask:0xf
	global_store_dwordx4 v[182:183], v[200:203], off offset:-3584
	global_store_dwordx4 v[182:183], v[204:207], off offset:-2560
	global_store_dwordx4 v[182:183], v[208:211], off offset:-1536
	global_store_dwordx4 v[182:183], v[212:215], off offset:-512
	v_lshl_add_u64 v[54:55], v[54:55], 0, s[42:43]
	s_cbranch_scc1 .LBB0_316
; __device__ __forceinline__ void norm_phase(const Args& a, const float* x, int layer, int which  , bool with_ctx) {
;     ...
;     for (int chunk = gw; chunk < M_ / 32; chunk += NGW) { const int row = chunk * 32, b = row / SEQ; const float* mb = MOD + (size_t)b * 6144;
;         norm_rows(x + (size_t)row * 1024, 32, g, mb + (c0 + 1) * 1024, mb + c0 * 1024, XN + (size_t)row * 1024, lane); }
;     if (with_ctx) { const float* mb = MOD + (size_t)8 * 6144;
;         for (int row = gw; row < MCTX; row += NGW) norm_rows(a.in[2] + (size_t)row * 1024, 1, g, mb + (c0 + 1) * 1024, mb + c0 * 1024, XN + (size_t)(M_ + row) * 1024, lane); }
	v_add_u32_e32 v33, s10, v33
	v_cmp_lt_i32_e32 vcc, s46, v33
	s_or_b64 s[12:13], vcc, s[12:13]
	v_add_u32_e32 v50, s11, v50
	s_andn2_b64 exec, exec, s[12:13]
	s_cbranch_execnz .LBB0_315
	s_or_b64 exec, exec, s[12:13]
	s_add_u32 s0, s28, 0x30000
	s_addc_u32 s1, s29, 0
	v_ashrrev_i32_e32 v33, 31, v32
	v_mov_b32_e32 v39, 0
	s_add_u32 s4, s28, 0x31000
	v_lshlrev_b64 v[18:19], 12, v[32:33]
	s_addc_u32 s5, s29, 0
	v_mov_b32_e32 v47, v39
	v_mov_b32_e32 v45, v39
	v_mov_b32_e32 v43, v39
	v_mov_b32_e32 v41, v39
	v_or_b32_e32 v18, v18, v36
	s_ashr_i32 s11, s10, 31
	v_lshl_add_u64 v[0:1], s[16:17], 0, v[38:39]
	v_lshl_add_u64 v[2:3], s[4:5], 0, v[46:47]
	v_lshl_add_u64 v[4:5], s[0:1], 0, v[46:47]
	v_lshl_add_u64 v[6:7], s[4:5], 0, v[44:45]
	v_lshl_add_u64 v[8:9], s[0:1], 0, v[44:45]
	v_lshl_add_u64 v[10:11], s[4:5], 0, v[42:43]
	v_lshl_add_u64 v[12:13], s[0:1], 0, v[42:43]
	v_lshl_add_u64 v[14:15], s[4:5], 0, v[40:41]
	v_lshl_add_u64 v[16:17], s[0:1], 0, v[40:41]
	v_lshl_add_u64 v[18:19], s[40:41], 0, v[18:19]
	s_lshl_b64 s[0:1], s[10:11], 12
	s_mov_b64 s[4:5], 0
	v_mov_b32_e32 v20, 0x358637bd
	s_mov_b32 s6, 0x800000
	s_movk_i32 s7, 0x7ff
